# per-tile next-tile mapping: generic division by the group size (always 4) replaced by shift/mask (drops a float-reciprocal + readfirstlane chain per tile)
# baseline (speedup 1.0000x reference)
.LBB0_159:
	s_add_i32 s85, s85, 1
	s_mul_i32 s0, s85, s79
	s_mul_hi_u32 s1, s85, s3
	s_add_i32 s1, s1, s0
	s_mul_i32 s0, s85, s3
	s_add_u32 s24, s0, s2
	s_addc_u32 s25, s1, s80
	v_cmp_gt_i64_e32 vcc, s[24:25], v[156:157]
	v_cmp_lt_i64_e64 s[0:1], s[24:25], v[154:155]
	s_cbranch_vccnz .LBB0_161
	s_ashr_i32 s10, s24, 31
	s_lshr_b32 s10, s10, 29
	s_add_i32 s10, s24, s10
	s_ashr_i32 s20, s10, 3
	s_and_b32 s10, s10, -8
	s_sub_i32 s10, s24, s10
	s_cmp_lt_i32 s10, 0
	s_cselect_b32 s21, s81, 0x160
	s_mul_i32 s10, s10, s21
	s_add_i32 s10, s10, s20
	s_mul_hi_i32 s20, s10, 0x2e8ba2e9
	s_lshr_b32 s21, s20, 31
	s_ashr_i32 s20, s20, 4
	s_add_i32 s20, s20, s21
	s_lshl_b32 s21, s20, 2
	s_sub_i32 s22, 0x80, s21
	s_min_i32 s22, s22, 4
	s_mulk_i32 s20, 0x58
	s_sub_i32 s10, s10, s20
	s_lshr_b32 s20, s10, 2
	s_and_b32 s10, s10, 3
	s_add_i32 s22, s21, s10

.LBB0_608:
	s_ashr_i32 s0, s18, 3
	s_add_i32 s0, s20, s0
	s_ashr_i32 s1, s0, 31
	s_lshr_b32 s1, s1, 28
	s_add_i32 s1, s0, s1
	s_ashr_i32 s18, s1, 4
	s_lshl_b32 s19, s18, 2
	s_sub_i32 s18, 0x80, s19
	s_min_i32 s20, s18, 4
	s_and_b32 s1, s1, -16
	s_sub_i32 s0, s0, s1
	s_lshr_b32 s18, s0, 2
	s_and_b32 s0, s0, 3
	s_add_i32 s83, s19, s0

.LBB0_712:
	s_ashr_i32 s10, s10, 3
	s_add_i32 s10, s22, s10
	s_ashr_i32 s19, s10, 31
	s_lshr_b32 s19, s19, 28
	s_add_i32 s19, s10, s19
	s_ashr_i32 s20, s19, 4
	s_lshl_b32 s21, s20, 2
	s_sub_i32 s20, 0x80, s21
	s_min_i32 s22, s20, 4
	s_and_b32 s19, s19, -16
	s_sub_i32 s10, s10, s19
	s_lshr_b32 s20, s10, 2
	s_and_b32 s10, s10, 3
	s_add_i32 s22, s21, s10

.LBB0_803:
	s_add_i32 s71, s71, 1
	s_mul_i32 s0, s71, s67
	s_mul_hi_u32 s1, s71, s3
	s_add_i32 s1, s1, s0
	s_mul_i32 s0, s71, s3
	s_add_u32 s22, s0, s2
	s_addc_u32 s23, s1, s55
	v_cmp_gt_i64_e32 vcc, s[22:23], v[146:147]
	v_cmp_lt_i64_e64 s[0:1], s[22:23], v[144:145]
	s_cbranch_vccnz .LBB0_805
	s_ashr_i32 s8, s22, 31
	s_lshr_b32 s8, s8, 29
	s_add_i32 s8, s22, s8
	s_ashr_i32 s18, s8, 3
	s_and_b32 s8, s8, -8
	s_sub_i32 s8, s22, s8
	s_cmp_lt_i32 s8, 0
	s_cselect_b32 s19, s56, 0x160
	s_mul_i32 s8, s8, s19
	s_add_i32 s8, s8, s18
	s_mul_hi_i32 s18, s8, 0x2e8ba2e9
	s_lshr_b32 s19, s18, 31
	s_ashr_i32 s18, s18, 4
	s_add_i32 s18, s18, s19
	s_lshl_b32 s19, s18, 2
	s_sub_i32 s20, 0x80, s19
	s_min_i32 s20, s20, 4
	s_mulk_i32 s18, 0x58
	s_sub_i32 s8, s8, s18
	s_lshr_b32 s18, s8, 2
	s_and_b32 s8, s8, 3
	s_add_i32 s20, s19, s8

.LBB0_890:
	s_ashr_i32 s6, s8, 3
	s_add_i32 s6, s19, s6
	s_ashr_i32 s7, s6, 31
	s_lshr_b32 s7, s7, 28
	s_add_i32 s7, s6, s7
	s_ashr_i32 s8, s7, 4
	s_lshl_b32 s8, s8, 2
	s_sub_i32 s18, 0x80, s8
	s_min_i32 s18, s18, 4
	s_and_b32 s7, s7, -16
	s_sub_i32 s6, s6, s7
	s_lshr_b32 s67, s6, 2
	s_and_b32 s6, s6, 3
	s_add_i32 s68, s8, s6

.LBB0_994:
	s_ashr_i32 s22, s24, 3
	s_add_i32 s22, s28, s22
	s_ashr_i32 s23, s22, 31
	s_lshr_b32 s23, s23, 28
	s_add_i32 s23, s22, s23
	s_ashr_i32 s24, s23, 4
	s_lshl_b32 s24, s24, 2
	s_sub_i32 s25, 0x80, s24
	s_min_i32 s25, s25, 4
	s_and_b32 s23, s23, -16
	s_sub_i32 s23, s22, s23
	s_lshr_b32 s22, s23, 2
	s_and_b32 s23, s23, 3
	s_add_i32 s24, s24, s23

.LBB0_1016:
	s_ashr_i32 s10, s10, 3
	s_add_i32 s10, s19, s10
	s_ashr_i32 s16, s10, 31
	s_lshr_b32 s16, s16, 28
	s_add_i32 s16, s10, s16
	s_ashr_i32 s17, s16, 4
	s_lshl_b32 s17, s17, 2
	s_sub_i32 s18, 0x80, s17
	s_min_i32 s18, s18, 4
	s_and_b32 s16, s16, -16
	s_sub_i32 s10, s10, s16
	s_lshr_b32 s16, s10, 2
	s_and_b32 s10, s10, 3
	s_add_i32 s18, s17, s10
